# nt cache policy also on the layer-1 norm residual loads and the modulation GEMV weight loads
# speedup vs baseline: 1.0281x; 1.0025x over previous
.LBB0_12:
	v_add_co_u32_e32 v12, vcc, 0x3000, v6
	s_mov_b64 s[2:3], vcc
	v_add_co_u32_e32 v14, vcc, 0x6000, v6
	s_mov_b64 s[4:5], vcc
	v_addc_co_u32_e64 v13, vcc, 0, v7, s[2:3]
	v_add_co_u32_e32 v16, vcc, 0x9000, v6
	s_mov_b64 s[2:3], vcc
	v_addc_co_u32_e64 v15, vcc, 0, v7, s[4:5]
	global_load_dword v2, v[12:13], off nt
	global_load_dword v44, v[14:15], off nt
	v_add_co_u32_e32 v12, vcc, 0xc000, v6
	s_mov_b64 s[4:5], vcc
	v_addc_co_u32_e64 v17, vcc, 0, v7, s[2:3]
	v_add_co_u32_e32 v14, vcc, 0xf000, v6
	s_mov_b64 s[2:3], vcc
	v_addc_co_u32_e64 v13, vcc, 0, v7, s[4:5]
	global_load_dword v46, v[16:17], off nt
	v_add_co_u32_e32 v16, vcc, 0x12000, v6
	s_mov_b64 s[4:5], vcc
	v_addc_co_u32_e64 v15, vcc, 0, v7, s[2:3]
	global_load_dword v48, v[12:13], off nt
	global_load_dword v50, v[14:15], off nt
	v_add_co_u32_e32 v12, vcc, 0x15000, v6
	s_mov_b64 s[2:3], vcc
	v_addc_co_u32_e64 v17, vcc, 0, v7, s[4:5]
	v_add_co_u32_e32 v14, vcc, 0x18000, v6
	s_mov_b64 s[4:5], vcc
	v_addc_co_u32_e64 v13, vcc, 0, v7, s[2:3]
	global_load_dword v52, v[16:17], off nt
	v_add_co_u32_e32 v16, vcc, 0x1b000, v6
	s_mov_b64 s[2:3], vcc
	v_addc_co_u32_e64 v15, vcc, 0, v7, s[4:5]
	global_load_dword v54, v[12:13], off nt
	global_load_dword v56, v[14:15], off nt
	v_add_co_u32_e32 v12, vcc, 0x1e000, v6
	s_mov_b64 s[4:5], vcc
	v_addc_co_u32_e64 v17, vcc, 0, v7, s[2:3]
	v_add_co_u32_e32 v14, vcc, 0x21000, v6
	s_mov_b64 s[2:3], vcc
	v_addc_co_u32_e64 v13, vcc, 0, v7, s[4:5]
	v_add_co_u32_e32 v18, vcc, 0x24000, v6
	s_mov_b64 s[4:5], vcc
	v_add_co_u32_e32 v20, vcc, 0x27000, v6
	s_mov_b64 s[6:7], vcc
	v_add_co_u32_e32 v22, vcc, 0x2a000, v6
	s_mov_b64 s[8:9], vcc
	v_add_co_u32_e32 v24, vcc, 0x2d000, v6
	s_add_i32 s28, s28, 16
	s_nop 0
	v_addc_co_u32_e32 v25, vcc, 0, v7, vcc
	global_load_dword v58, v[24:25], off nt
	global_load_dword v60, v[6:7], off nt
	global_load_dword v62, v[16:17], off nt
	global_load_dword v64, v[12:13], off nt
	v_addc_co_u32_e64 v15, vcc, 0, v7, s[2:3]
	v_addc_co_u32_e64 v19, vcc, 0, v7, s[4:5]
	global_load_dword v66, v[14:15], off nt
	global_load_dword v68, v[18:19], off nt
	v_addc_co_u32_e64 v21, vcc, 0, v7, s[6:7]
	v_addc_co_u32_e64 v23, vcc, 0, v7, s[8:9]
	global_load_dword v70, v[20:21], off nt
	global_load_dword v72, v[22:23], off nt
	ds_read_b128 v[12:15], v10
	ds_read_b128 v[16:19], v10 offset:16
	ds_read_b128 v[20:23], v10 offset:32
	ds_read_b128 v[24:27], v10 offset:48
	ds_read_b128 v[28:31], v10 offset:4112
	ds_read_b128 v[32:35], v10 offset:4096
	ds_read_b128 v[36:39], v10 offset:4128
	ds_read_b128 v[40:43], v10 offset:4144
	s_waitcnt lgkmcnt(7)
	v_mov_b32_e32 v74, v12
	v_mov_b32_e32 v12, v14
	s_waitcnt lgkmcnt(2)
	v_mov_b32_e32 v75, v32
	v_mov_b32_e32 v32, v13
	v_mov_b32_e32 v13, v34
	v_mov_b32_e32 v34, v15
	v_mov_b32_e32 v14, v16
	v_mov_b32_e32 v15, v28
	v_mov_b32_e32 v28, v17
	v_mov_b32_e32 v16, v18
	v_mov_b32_e32 v17, v30
	v_mov_b32_e32 v30, v19
	v_mov_b32_e32 v18, v20
	s_waitcnt lgkmcnt(1)
	v_mov_b32_e32 v19, v36
	v_mov_b32_e32 v36, v21
	v_mov_b32_e32 v20, v22
	v_mov_b32_e32 v21, v38
	v_mov_b32_e32 v38, v23
	v_mov_b32_e32 v22, v24
	s_waitcnt lgkmcnt(0)
	v_mov_b32_e32 v23, v40
	v_mov_b32_e32 v40, v25
	v_mov_b32_e32 v24, v26
	v_mov_b32_e32 v25, v42
	v_mov_b32_e32 v42, v27
	v_add_u32_e32 v10, 64, v10
	s_cmpk_lt_u32 s28, 0x70
	v_lshl_add_u64 v[6:7], v[6:7], 0, s[20:21]
	s_waitcnt vmcnt(6)
	v_pk_fma_f32 v[4:5], v[60:61], v[74:75], v[4:5] op_sel_hi:[0,1,1]
	v_pk_fma_f32 v[4:5], v[2:3], v[32:33], v[4:5] op_sel_hi:[0,1,1]
	v_pk_fma_f32 v[4:5], v[44:45], v[12:13], v[4:5] op_sel_hi:[0,1,1]
	v_pk_fma_f32 v[4:5], v[46:47], v[34:35], v[4:5] op_sel_hi:[0,1,1]
	v_pk_fma_f32 v[4:5], v[48:49], v[14:15], v[4:5] op_sel_hi:[0,1,1]
	v_pk_fma_f32 v[4:5], v[50:51], v[28:29], v[4:5] op_sel_hi:[0,1,1]
	v_pk_fma_f32 v[4:5], v[52:53], v[16:17], v[4:5] op_sel_hi:[0,1,1]
	v_pk_fma_f32 v[4:5], v[54:55], v[30:31], v[4:5] op_sel_hi:[0,1,1]
	v_pk_fma_f32 v[4:5], v[56:57], v[18:19], v[4:5] op_sel_hi:[0,1,1]
	s_waitcnt vmcnt(5)
	v_pk_fma_f32 v[4:5], v[62:63], v[36:37], v[4:5] op_sel_hi:[0,1,1]
	s_waitcnt vmcnt(4)
	v_pk_fma_f32 v[4:5], v[64:65], v[20:21], v[4:5] op_sel_hi:[0,1,1]
	s_waitcnt vmcnt(3)
	v_pk_fma_f32 v[4:5], v[66:67], v[38:39], v[4:5] op_sel_hi:[0,1,1]
	s_waitcnt vmcnt(2)
	v_pk_fma_f32 v[4:5], v[68:69], v[22:23], v[4:5] op_sel_hi:[0,1,1]
	s_waitcnt vmcnt(1)
	v_pk_fma_f32 v[4:5], v[70:71], v[40:41], v[4:5] op_sel_hi:[0,1,1]
	s_waitcnt vmcnt(0)
	v_pk_fma_f32 v[4:5], v[72:73], v[24:25], v[4:5] op_sel_hi:[0,1,1]
	v_pk_fma_f32 v[4:5], v[58:59], v[42:43], v[4:5] op_sel_hi:[0,1,1]
	s_cbranch_scc1 .LBB0_12
	v_lshl_add_u32 v2, v1, 3, s1
	v_cmp_gt_u32_e32 vcc, 64, v1
	ds_write_b64 v2, v[4:5]
	s_waitcnt lgkmcnt(0)
	s_barrier
	s_and_saveexec_b64 s[2:3], vcc
	s_cbranch_execz .LBB0_10
	s_mul_i32 s4, s27, 0xc00
	s_add_i32 s4, s4, s22
	v_or_b32_e32 v4, s4, v8
	v_ashrrev_i32_e32 v5, 31, v4
	v_lshl_add_u64 v[4:5], v[4:5], 2, s[14:15]
	global_load_dword v1, v[4:5], off
	v_lshlrev_b32_e32 v2, 3, v8
	v_lshlrev_b32_e32 v4, 2, v9
	v_lshl_or_b32 v5, s27, 1, v9
	v_add3_u32 v2, s1, v2, v4
	v_mul_lo_u32 v9, v5, s25
	ds_read2st64_b32 v[4:5], v2 offset1:1
	ds_read2st64_b32 v[6:7], v2 offset0:2 offset1:3
	ds_read2st64_b32 v[10:11], v2 offset0:4 offset1:5
	ds_read2st64_b32 v[12:13], v2 offset0:6 offset1:7
	v_add_u32_e32 v2, s22, v9
	v_or_b32_e32 v8, v2, v8
	s_waitcnt lgkmcnt(3)
	v_add_f32_e32 v2, 0, v4
	v_add_f32_e32 v2, v2, v5
	s_waitcnt lgkmcnt(2)
	v_add_f32_e32 v2, v2, v6
	v_add_f32_e32 v2, v2, v7
	s_waitcnt lgkmcnt(1)
	v_add_f32_e32 v2, v2, v10
	v_add_f32_e32 v2, v2, v11
	s_waitcnt lgkmcnt(0)
	v_add_f32_e32 v2, v2, v12
	v_ashrrev_i32_e32 v9, 31, v8
	v_add_f32_e32 v2, v2, v13
	v_lshl_add_u64 v[4:5], v[8:9], 2, s[18:19]
	s_waitcnt vmcnt(0)
	v_add_f32_e32 v1, v2, v1
	global_store_dword v[4:5], v1, off
	s_branch .LBB0_10

.LBB0_794:
	v_mov_b32_e32 v0, v198
	s_ashr_i32 s8, s1, 11
	v_and_b32_e32 v17, 63, v0
	v_bfe_u32 v0, v0, 6, 2
	v_add_u32_e32 v6, s14, v0
	v_ashrrev_i32_e32 v7, 31, v6
	v_lshlrev_b64 v[0:1], 12, v[6:7]
	v_lshl_add_u64 v[0:1], s[52:53], 0, v[0:1]
	v_lshlrev_b32_e32 v4, 4, v17
	v_lshl_add_u64 v[0:1], v[0:1], 0, v[4:5]
	global_load_dwordx4 v[20:23], v[0:1], off nt
	global_load_dwordx4 v[24:27], v[0:1], off offset:1024 nt
	global_load_dwordx4 v[28:31], v[0:1], off offset:2048 nt
	s_nop 0
	global_load_dwordx4 v[0:3], v[0:1], off offset:3072 nt
	s_mulk_i32 s8, 0xc00
	s_addk_i32 s8, 0x1800
	s_ashr_i32 s9, s8, 31
	s_lshl_b64 s[8:9], s[8:9], 2
	s_add_u32 s8, s12, s8
	s_addc_u32 s9, s13, s9
	s_add_u32 s10, s8, 0x1000
	s_addc_u32 s11, s9, 0
	global_load_dwordx4 v[32:35], v4, s[10:11]
	global_load_dwordx4 v[36:39], v4, s[4:5]
	global_load_dwordx4 v[40:43], v4, s[8:9]
	v_or_b32_e32 v100, 0x400, v4
	v_or_b32_e32 v101, 0x800, v4
	v_or_b32_e32 v102, 0xc00, v4
	global_load_dwordx4 v[64:67], v100, s[4:5]
	global_load_dwordx4 v[68:71], v100, s[10:11]
	global_load_dwordx4 v[72:75], v4, s[8:9] offset:1024
	global_load_dwordx4 v[76:79], v101, s[4:5]
	global_load_dwordx4 v[80:83], v101, s[10:11]
	global_load_dwordx4 v[84:87], v4, s[8:9] offset:2048
	global_load_dwordx4 v[88:91], v102, s[4:5]
	global_load_dwordx4 v[92:95], v102, s[10:11]
	global_load_dwordx4 v[96:99], v4, s[8:9] offset:3072
	v_cmp_lt_i32_e32 vcc, v10, v9
	s_waitcnt vmcnt(15)
	v_mov_b32_e32 v46, v21
	v_cndmask_b32_e32 v44, v8, v10, vcc
	s_waitcnt vmcnt(14)
	v_mov_b32_e32 v47, v25
	v_lshlrev_b32_e32 v60, 2, v44
	v_mov_b32_e32 v44, v20
	v_mov_b32_e32 v45, v24
	s_waitcnt vmcnt(13)
	v_mov_b32_e32 v54, v29
	s_waitcnt vmcnt(12)
	v_mov_b32_e32 v55, v1
	v_pk_mul_f32 v[46:47], v[46:47], v[46:47]
	v_mov_b32_e32 v48, v22
	v_mov_b32_e32 v49, v26
	v_mov_b32_e32 v52, v28
	v_mov_b32_e32 v53, v0
	v_pk_mul_f32 v[54:55], v[54:55], v[54:55]
	v_pk_fma_f32 v[44:45], v[44:45], v[44:45], v[46:47]
	v_mov_b32_e32 v50, v23
	v_mov_b32_e32 v51, v27
	v_mov_b32_e32 v56, v30
	v_mov_b32_e32 v57, v2
	v_pk_fma_f32 v[46:47], v[52:53], v[52:53], v[54:55]
	v_pk_fma_f32 v[44:45], v[48:49], v[48:49], v[44:45]
	v_mov_b32_e32 v58, v31
	v_mov_b32_e32 v59, v3
	v_pk_fma_f32 v[46:47], v[56:57], v[56:57], v[46:47]
	v_pk_fma_f32 v[44:45], v[50:51], v[50:51], v[44:45]
	v_pk_fma_f32 v[46:47], v[58:59], v[58:59], v[46:47]
	v_add_f32_e32 v44, v44, v45
	v_add_f32_e32 v44, v44, v46
	v_add_f32_e32 v44, v44, v47
	ds_bpermute_b32 v45, v60, v44
	v_cmp_lt_i32_e32 vcc, v11, v9
	s_waitcnt vmcnt(11)
	v_pk_add_f32 v[32:33], v[32:33], 1.0 op_sel_hi:[1,0]
	v_pk_add_f32 v[34:35], v[34:35], 1.0 op_sel_hi:[1,0]
	v_cndmask_b32_e32 v46, v8, v11, vcc
	v_lshlrev_b32_e32 v46, 2, v46
	s_waitcnt lgkmcnt(0)
	v_add_f32_e32 v44, v44, v45
	ds_bpermute_b32 v45, v46, v44
	v_cmp_lt_i32_e32 vcc, v12, v9
	v_or_b32_e32 v50, 0x400, v4
	s_waitcnt lgkmcnt(0)
	v_add_f32_e32 v44, v44, v45
	v_cndmask_b32_e32 v46, v8, v12, vcc
	v_lshlrev_b32_e32 v46, 2, v46
	ds_bpermute_b32 v45, v46, v44
	v_cmp_lt_i32_e32 vcc, v13, v9
	s_waitcnt lgkmcnt(0)
	v_add_f32_e32 v44, v44, v45
	v_cndmask_b32_e32 v46, v8, v13, vcc
	v_lshlrev_b32_e32 v46, 2, v46
	ds_bpermute_b32 v45, v46, v44
	v_cmp_lt_i32_e32 vcc, v14, v9
	s_waitcnt lgkmcnt(0)
	v_add_f32_e32 v44, v44, v45
	v_cndmask_b32_e32 v46, v8, v14, vcc
	v_lshlrev_b32_e32 v46, 2, v46
	ds_bpermute_b32 v46, v46, v44
	v_cmp_lt_i32_e32 vcc, v15, v9
	v_mov_b32_e32 v45, v5
	s_waitcnt lgkmcnt(0)
	v_add_f32_e32 v48, v44, v46
	v_cndmask_b32_e32 v47, v8, v15, vcc
	v_lshlrev_b32_e32 v47, 2, v47
	ds_bpermute_b32 v49, v47, v48
	v_lshlrev_b64 v[46:47], 11, v[6:7]
	v_lshlrev_b32_e32 v44, 3, v17
	v_lshl_add_u64 v[46:47], s[2:3], 0, v[46:47]
	v_lshl_add_u64 v[44:45], v[46:47], 0, v[44:45]
	s_waitcnt lgkmcnt(0)
	v_add_f32_e32 v7, v48, v49
	v_fmamk_f32 v7, v7, 0x3a800000, v16
	v_mul_f32_e32 v48, 0x4b800000, v7
	v_cmp_gt_f32_e32 vcc, s16, v7
	s_nop 1
	v_cndmask_b32_e32 v7, v7, v48, vcc
	v_rsq_f32_e32 v7, v7
	s_nop 0
	v_mul_f32_e32 v46, 0x45800000, v7
	v_cndmask_b32_e32 v46, v7, v46, vcc
	v_pk_mul_f32 v[20:21], v[20:21], v[46:47] op_sel_hi:[1,0]
	v_pk_mul_f32 v[22:23], v[22:23], v[46:47] op_sel_hi:[1,0]
	s_waitcnt vmcnt(10)
	v_pk_mul_f32 v[20:21], v[36:37], v[20:21]
	v_pk_mul_f32 v[22:23], v[38:39], v[22:23]
	s_waitcnt vmcnt(9)
	v_pk_fma_f32 v[20:21], v[32:33], v[20:21], v[40:41]
	v_pk_fma_f32 v[22:23], v[34:35], v[22:23], v[42:43]
	v_cvt_pk_bf16_f32 v20, v20, v21
	v_cvt_pk_bf16_f32 v21, v22, v23
	global_store_dwordx2 v[44:45], v[20:21], off
	v_pk_mul_f32 v[24:25], v[24:25], v[46:47] op_sel_hi:[1, 0]
	v_pk_mul_f32 v[26:27], v[26:27], v[46:47] op_sel_hi:[1, 0]
	v_or_b32_e32 v7, 0x800, v4
	v_pk_mul_f32 v[28:29], v[28:29], v[46:47] op_sel_hi:[1, 0]
	v_pk_mul_f32 v[30:31], v[30:31], v[46:47] op_sel_hi:[1, 0]
	v_pk_mul_f32 v[0:1], v[0:1], v[46:47] op_sel_hi:[1, 0]
	v_pk_mul_f32 v[2:3], v[2:3], v[46:47] op_sel_hi:[1, 0]
	v_cmp_eq_u32_e32 vcc, 0, v17
	s_waitcnt vmcnt(9)
	v_pk_mul_f32 v[20:21], v[64:65], v[24:25]
	s_waitcnt vmcnt(8)
	v_pk_add_f32 v[24:25], v[68:69], 1.0 op_sel_hi:[1, 0]
	v_pk_mul_f32 v[22:23], v[66:67], v[26:27]
	v_pk_add_f32 v[26:27], v[70:71], 1.0 op_sel_hi:[1, 0]
	s_waitcnt vmcnt(7)
	v_pk_fma_f32 v[20:21], v[24:25], v[20:21], v[72:73]
	v_pk_fma_f32 v[22:23], v[26:27], v[22:23], v[74:75]
	v_cvt_pk_bf16_f32 v20, v20, v21
	v_cvt_pk_bf16_f32 v21, v22, v23
	global_store_dwordx2 v[44:45], v[20:21], off offset:512
	v_or_b32_e32 v7, 0xc00, v4
	s_waitcnt vmcnt(7)
	v_pk_mul_f32 v[20:21], v[28:29], v[76:77]
	s_waitcnt vmcnt(6)
	v_pk_add_f32 v[24:25], v[80:81], 1.0 op_sel_hi:[1, 0]
	v_pk_mul_f32 v[22:23], v[30:31], v[78:79]
	v_pk_add_f32 v[26:27], v[82:83], 1.0 op_sel_hi:[1, 0]
	s_waitcnt vmcnt(5)
	v_pk_fma_f32 v[20:21], v[20:21], v[24:25], v[84:85]
	v_pk_fma_f32 v[22:23], v[22:23], v[26:27], v[86:87]
	v_cvt_pk_bf16_f32 v20, v20, v21
	v_cvt_pk_bf16_f32 v21, v22, v23
	global_store_dwordx2 v[44:45], v[20:21], off offset:1024
	s_waitcnt vmcnt(5)
	v_pk_mul_f32 v[0:1], v[0:1], v[88:89]
	s_waitcnt vmcnt(4)
	v_pk_add_f32 v[20:21], v[92:93], 1.0 op_sel_hi:[1, 0]
	v_pk_mul_f32 v[2:3], v[2:3], v[90:91]
	v_pk_add_f32 v[22:23], v[94:95], 1.0 op_sel_hi:[1, 0]
	s_waitcnt vmcnt(3)
	v_pk_fma_f32 v[0:1], v[0:1], v[20:21], v[96:97]
	v_pk_fma_f32 v[2:3], v[2:3], v[22:23], v[98:99]
	v_cvt_pk_bf16_f32 v0, v0, v1
	v_cvt_pk_bf16_f32 v1, v2, v3
	global_store_dwordx2 v[44:45], v[0:1], off offset:1536
	s_and_saveexec_b64 s[8:9], vcc
	s_cbranch_execz .LBB0_793
	v_lshlrev_b32_e32 v0, 1, v6
	v_ashrrev_i32_e32 v1, 31, v0
	v_lshl_add_u64 v[0:1], v[0:1], 2, s[6:7]
	global_store_dwordx2 v[0:1], v[18:19], off
	s_branch .LBB0_793
